# stack9 + prologue weight-transpose items re-ordered per matrix (n-band major, all k-blocks of a band concurrently) so each bf16 output row is written completely within one sweep
# speedup vs baseline: 1.0056x; 1.0015x over previous
; #define GAS __attribute__((address_space(1)))
; #define INP(k) (*(const float* const __attribute__((address_space(4)))*)(ka + 8 * (k)))
; __device__ __forceinline__ void p0_transpose_item(const float* W, int K, int N, bf16* WT, LAS float* scr, int item, int lane) {
;     const int nblk = N / 32, kb = item / nblk, nb = item % nblk, k0 = 64 * kb, n0 = 32 * nb;
; #pragma unroll 8
;     for (int i = 0; i < 32; ++i) { const int kk = 2 * i + (lane >> 5); scr[kk * 33 + (lane & 31)] = ((const GAS float*)W)[(size_t)(k0 + kk) * N + n0 + (lane & 31)]; }
; __device__ __forceinline__ void phase_prologue(Frame& F) {
;     ...
;         const int l = it / PER_L; int r = it % PER_L;
;         if (r < I_IN) { p0_transpose_item(INP(6) + (size_t)l * D * DIN, D, DIN, (bf16*)(ws_ + WS_WIN + l * SZ_WIN), scr, r, lane); continue; } r -= I_IN;
;         if (r < I_OC) { p0_transpose_item(INP(19) + (size_t)l * DC * D, DC, D, (bf16*)(ws_ + WS_WOC + l * SZ_WOC), scr, r, lane); continue; } r -= I_OC;
;         if (r < I_OC) { p0_transpose_item(INP(20) + (size_t)l * DC * D, DC, D, (bf16*)(ws_ + WS_WOR + l * SZ_WOC), scr, r, lane); continue; } r -= I_OC;
;         if (r < I_O) { p0_transpose_item(INP(21) + (size_t)l * D * D, D, D, (bf16*)(ws_ + WS_WO + l * SZ_WO), scr, r, lane); continue; } r -= I_O;
;         if (r < I_UP) { p0_transpose_item(INP(23) + (size_t)l * D * DFF, D, DFF, (bf16*)(ws_ + WS_WUP + l * SZ_WUP), scr, r, lane); continue; } r -= I_UP;
;         p0_transpose_item(INP(24) + (size_t)l * DFF * D, DFF, D, (bf16*)(ws_ + WS_WDN + l * SZ_WUP), scr, r, lane);
.LBB0_25:
	s_cmpk_gt_u32 s29, 0x2cff
	s_cbranch_scc0 .LBB0_47
	s_cmpk_gt_u32 s29, 0x30ff
	s_cbranch_scc0 .LBB0_42
	s_cmpk_gt_u32 s29, 0x38ff
	s_cbranch_scc0 .LBB0_37
	s_ashr_i32 s7, s6, 31
	s_lshl_b64 s[12:13], s[6:7], 26
	s_lshl_b64 s[8:9], s[6:7], 25
	s_cmpk_gt_u32 s29, 0x58ff
	s_mov_b64 s[14:15], -1
	s_cbranch_scc0 .LBB0_32
	s_sub_i32 s98, s29, 0x5900
	s_bfe_u32 s99, s98, 0x70003
	s_lshr_b32 s100, s98, 10
	s_and_b32 s98, s98, 7
	s_lshl_b32 s100, s100, 3
	s_mul_i32 s99, s99, 0x40
	s_add_i32 s99, s99, s100
	s_add_i32 s99, s99, s98
	s_add_i32 s29, s99, 0x5900
	s_load_dwordx2 s[14:15], s[10:11], 0xc0
	s_waitcnt lgkmcnt(0)
	s_add_u32 s30, s14, s12
	s_addc_u32 s15, s15, s13
	s_add_i32 s7, s29, 0xa700
	s_lshl_b32 s31, s29, 5
	s_and_b32 s14, s7, 0xffc0
	s_and_b32 s7, s31, 0x7e0
	s_lshl_b32 s31, s7, 2
	s_add_u32 s30, s30, s31
	s_addc_u32 s31, s15, 0
	v_add_u32_e32 v19, s14, v1
	v_lshl_add_u64 v[22:23], s[30:31], 0, v[2:3]
	v_add_u32_e32 v24, s14, v0
	v_add_u32_e32 v21, s14, v5
	v_add_u32_e32 v26, s14, v8
	v_add_u32_e32 v25, s14, v7
	v_add_u32_e32 v28, s14, v10
	v_add_u32_e32 v27, s14, v9
	v_add_u32_e32 v30, s14, v12
	v_add_u32_e32 v29, s14, v11
	v_add_u32_e32 v32, s14, v14
	v_add_u32_e32 v31, s14, v13
	v_add_u32_e32 v34, s14, v16
	s_mov_b32 s15, 1
	s_mov_b32 s30, 0
	s_mov_b32 s31, 32
	v_add_u32_e32 v33, s14, v15
	v_add_u32_e32 v36, s14, v18
	v_add_u32_e32 v35, s14, v17
	v_add_u32_e32 v38, s14, v20

; #define GAS __attribute__((address_space(1)))
; #define INP(k) (*(const float* const __attribute__((address_space(4)))*)(ka + 8 * (k)))
; __device__ __forceinline__ void p0_transpose_item(const float* W, int K, int N, bf16* WT, LAS float* scr, int item, int lane) {
;     const int nblk = N / 32, kb = item / nblk, nb = item % nblk, k0 = 64 * kb, n0 = 32 * nb;
; #pragma unroll 8
;     for (int i = 0; i < 32; ++i) { const int kk = 2 * i + (lane >> 5); scr[kk * 33 + (lane & 31)] = ((const GAS float*)W)[(size_t)(k0 + kk) * N + n0 + (lane & 31)]; }
; __device__ __forceinline__ void phase_prologue(Frame& F) {
;     ...
;         if (r < I_UP) { p0_transpose_item(INP(23) + (size_t)l * D * DFF, D, DFF, (bf16*)(ws_ + WS_WUP + l * SZ_WUP), scr, r, lane); continue; } r -= I_UP;
.LBB0_32:
	s_sub_i32 s98, s29, 0x3900
	s_bfe_u32 s99, s98, 0x50003
	s_lshr_b32 s100, s98, 8
	s_and_b32 s98, s98, 7
	s_lshl_b32 s100, s100, 3
	s_mul_i32 s99, s99, 0x100
	s_add_i32 s99, s99, s100
	s_add_i32 s99, s99, s98
	s_add_i32 s29, s99, 0x3900
	s_and_b64 vcc, exec, s[14:15]
	s_cbranch_vccz .LBB0_36
	s_load_dwordx2 s[14:15], s[10:11], 0xb8
	s_waitcnt lgkmcnt(0)
	s_add_u32 s14, s14, s12
	s_addc_u32 s13, s15, s13
	s_add_i32 s7, s29, 0xc700
	s_lshl_b32 s12, s29, 5
	s_bfe_u32 s15, s7, 0x80008
	s_and_b32 s7, s12, 0x1fe0
	s_lshl_b32 s12, s15, 6
	s_lshl_b32 s15, s7, 2
	s_add_u32 s14, s14, s15
	s_addc_u32 s15, s13, 0
	v_lshl_add_u64 v[22:23], s[14:15], 0, v[2:3]
	v_add_u32_e32 v19, s12, v1
	v_add_u32_e32 v24, s12, v0
	v_add_u32_e32 v21, s12, v5
	v_add_u32_e32 v26, s12, v8
	v_add_u32_e32 v25, s12, v7
	v_add_u32_e32 v28, s12, v10
	v_add_u32_e32 v27, s12, v9
	v_add_u32_e32 v30, s12, v12
	v_add_u32_e32 v29, s12, v11
	v_add_u32_e32 v32, s12, v14
	v_add_u32_e32 v31, s12, v13
	v_add_u32_e32 v34, s12, v16
	s_mov_b32 s13, 1
	s_mov_b32 s14, 0
	s_mov_b32 s15, 32
	v_add_u32_e32 v33, s12, v15
	v_add_u32_e32 v36, s12, v18
	v_add_u32_e32 v35, s12, v17
	v_add_u32_e32 v38, s12, v20

; #define GAS __attribute__((address_space(1)))
; #define INP(k) (*(const float* const __attribute__((address_space(4)))*)(ka + 8 * (k)))
; __device__ __forceinline__ void p0_transpose_item(const float* W, int K, int N, bf16* WT, LAS float* scr, int item, int lane) {
;     const int nblk = N / 32, kb = item / nblk, nb = item % nblk, k0 = 64 * kb, n0 = 32 * nb;
; #pragma unroll 8
;     for (int i = 0; i < 32; ++i) { const int kk = 2 * i + (lane >> 5); scr[kk * 33 + (lane & 31)] = ((const GAS float*)W)[(size_t)(k0 + kk) * N + n0 + (lane & 31)]; }
; __device__ __forceinline__ void phase_prologue(Frame& F) {
;     ...
;         if (r < I_O) { p0_transpose_item(INP(21) + (size_t)l * D * D, D, D, (bf16*)(ws_ + WS_WO + l * SZ_WO), scr, r, lane); continue; } r -= I_O;
.LBB0_37:
	s_sub_i32 s98, s29, 0x3100
	s_bfe_u32 s99, s98, 0x50003
	s_lshr_b32 s100, s98, 8
	s_and_b32 s98, s98, 7
	s_lshl_b32 s100, s100, 3
	s_mul_i32 s99, s99, 0x40
	s_add_i32 s99, s99, s100
	s_add_i32 s99, s99, s98
	s_add_i32 s29, s99, 0x3100
	s_andn2_b64 vcc, exec, s[8:9]
	s_cbranch_vccnz .LBB0_41
	s_load_dwordx2 s[8:9], s[10:11], 0xa8
	s_ashr_i32 s7, s6, 31
	s_lshl_b64 s[12:13], s[6:7], 24
	s_waitcnt lgkmcnt(0)
	s_add_u32 s12, s8, s12
	s_addc_u32 s13, s9, s13
	s_add_i32 s8, s29, 0xcf00
	s_lshl_b32 s14, s29, 5
	s_and_b32 s9, s8, 0xffc0
	s_and_b32 s8, s14, 0x7e0
	s_lshl_b32 s14, s8, 2
	s_add_u32 s12, s12, s14
	s_addc_u32 s13, s13, 0
	v_lshl_add_u64 v[22:23], s[12:13], 0, v[2:3]
	v_add_u32_e32 v19, s9, v1
	v_add_u32_e32 v24, s9, v0
	v_add_u32_e32 v21, s9, v5
	v_add_u32_e32 v26, s9, v8
	v_add_u32_e32 v25, s9, v7
	v_add_u32_e32 v28, s9, v10
	v_add_u32_e32 v27, s9, v9
	v_add_u32_e32 v30, s9, v12
	v_add_u32_e32 v29, s9, v11
	v_add_u32_e32 v32, s9, v14
	v_add_u32_e32 v31, s9, v13
	v_add_u32_e32 v34, s9, v16
	s_mov_b32 s12, 1
	s_mov_b32 s13, 0
	s_mov_b32 s14, 32
	v_add_u32_e32 v33, s9, v15
	v_add_u32_e32 v36, s9, v18
	v_add_u32_e32 v35, s9, v17
	v_add_u32_e32 v38, s9, v20

; #define GAS __attribute__((address_space(1)))
; #define INP(k) (*(const float* const __attribute__((address_space(4)))*)(ka + 8 * (k)))
; __device__ __forceinline__ void p0_transpose_item(const float* W, int K, int N, bf16* WT, LAS float* scr, int item, int lane) {
;     const int nblk = N / 32, kb = item / nblk, nb = item % nblk, k0 = 64 * kb, n0 = 32 * nb;
; #pragma unroll 8
;     for (int i = 0; i < 32; ++i) { const int kk = 2 * i + (lane >> 5); scr[kk * 33 + (lane & 31)] = ((const GAS float*)W)[(size_t)(k0 + kk) * N + n0 + (lane & 31)]; }
; __device__ __forceinline__ void phase_prologue(Frame& F) {
;     ...
;         if (r < I_OC) { p0_transpose_item(INP(20) + (size_t)l * DC * D, DC, D, (bf16*)(ws_ + WS_WOR + l * SZ_WOC), scr, r, lane); continue; } r -= I_OC;
.LBB0_42:
	s_sub_i32 s98, s29, 0x2d00
	s_bfe_u32 s99, s98, 0x40003
	s_lshr_b32 s100, s98, 7
	s_and_b32 s98, s98, 7
	s_lshl_b32 s100, s100, 3
	s_mul_i32 s99, s99, 0x40
	s_add_i32 s99, s99, s100
	s_add_i32 s99, s99, s98
	s_add_i32 s29, s99, 0x2d00
	s_andn2_b64 vcc, exec, s[8:9]
	s_cbranch_vccnz .LBB0_46
	s_load_dwordx2 s[8:9], s[10:11], 0xa0
	s_ashr_i32 s7, s6, 31
	s_lshl_b64 s[12:13], s[6:7], 23
	s_waitcnt lgkmcnt(0)
	s_add_u32 s12, s8, s12
	s_addc_u32 s13, s9, s13
	s_add_i32 s8, s29, 0xd300
	s_lshl_b32 s14, s29, 5
	s_and_b32 s9, s8, 0xffc0
	s_and_b32 s8, s14, 0x7e0
	s_lshl_b32 s14, s8, 2
	s_add_u32 s12, s12, s14
	s_addc_u32 s13, s13, 0
	v_lshl_add_u64 v[22:23], s[12:13], 0, v[2:3]
	v_add_u32_e32 v19, s9, v1
	v_add_u32_e32 v24, s9, v0
	v_add_u32_e32 v21, s9, v5
	v_add_u32_e32 v26, s9, v8
	v_add_u32_e32 v25, s9, v7
	v_add_u32_e32 v28, s9, v10
	v_add_u32_e32 v27, s9, v9
	v_add_u32_e32 v30, s9, v12
	v_add_u32_e32 v29, s9, v11
	v_add_u32_e32 v32, s9, v14
	v_add_u32_e32 v31, s9, v13
	v_add_u32_e32 v34, s9, v16
	s_mov_b32 s12, 1
	s_mov_b32 s13, 0
	s_mov_b32 s14, 32
	v_add_u32_e32 v33, s9, v15
	v_add_u32_e32 v36, s9, v18
	v_add_u32_e32 v35, s9, v17
	v_add_u32_e32 v38, s9, v20

; #define GAS __attribute__((address_space(1)))
; #define INP(k) (*(const float* const __attribute__((address_space(4)))*)(ka + 8 * (k)))
; __device__ __forceinline__ void p0_transpose_item(const float* W, int K, int N, bf16* WT, LAS float* scr, int item, int lane) {
;     const int nblk = N / 32, kb = item / nblk, nb = item % nblk, k0 = 64 * kb, n0 = 32 * nb;
; #pragma unroll 8
;     for (int i = 0; i < 32; ++i) { const int kk = 2 * i + (lane >> 5); scr[kk * 33 + (lane & 31)] = ((const GAS float*)W)[(size_t)(k0 + kk) * N + n0 + (lane & 31)]; }
; __device__ __forceinline__ void phase_prologue(Frame& F) {
;     ...
;         if (r < I_OC) { p0_transpose_item(INP(19) + (size_t)l * DC * D, DC, D, (bf16*)(ws_ + WS_WOC + l * SZ_WOC), scr, r, lane); continue; } r -= I_OC;
.LBB0_47:
	s_sub_i32 s98, s29, 0x2900
	s_bfe_u32 s99, s98, 0x40003
	s_lshr_b32 s100, s98, 7
	s_and_b32 s98, s98, 7
	s_lshl_b32 s100, s100, 3
	s_mul_i32 s99, s99, 0x40
	s_add_i32 s99, s99, s100
	s_add_i32 s99, s99, s98
	s_add_i32 s29, s99, 0x2900
	s_andn2_b64 vcc, exec, s[8:9]
	s_cbranch_vccnz .LBB0_51
	s_load_dwordx2 s[8:9], s[10:11], 0x98
	s_ashr_i32 s7, s6, 31
	s_lshl_b64 s[12:13], s[6:7], 23
	s_waitcnt lgkmcnt(0)
	s_add_u32 s12, s8, s12
	s_addc_u32 s13, s9, s13
	s_add_i32 s8, s29, 0xd700
	s_lshl_b32 s14, s29, 5
	s_and_b32 s9, s8, 0xffc0
	s_and_b32 s8, s14, 0x7e0
	s_lshl_b32 s14, s8, 2
	s_add_u32 s12, s12, s14
	s_addc_u32 s13, s13, 0
	v_lshl_add_u64 v[22:23], s[12:13], 0, v[2:3]
	v_add_u32_e32 v19, s9, v1
	v_add_u32_e32 v24, s9, v0
	v_add_u32_e32 v21, s9, v5
	v_add_u32_e32 v26, s9, v8
	v_add_u32_e32 v25, s9, v7
	v_add_u32_e32 v28, s9, v10
	v_add_u32_e32 v27, s9, v9
	v_add_u32_e32 v30, s9, v12
	v_add_u32_e32 v29, s9, v11
	v_add_u32_e32 v32, s9, v14
	v_add_u32_e32 v31, s9, v13
	v_add_u32_e32 v34, s9, v16
	s_mov_b32 s12, 1
	s_mov_b32 s13, 0
	s_mov_b32 s14, 32
	v_add_u32_e32 v33, s9, v15
	v_add_u32_e32 v36, s9, v18
	v_add_u32_e32 v35, s9, v17
	v_add_u32_e32 v38, s9, v20

; #define GAS __attribute__((address_space(1)))
; #define INP(k) (*(const float* const __attribute__((address_space(4)))*)(ka + 8 * (k)))
; __device__ __forceinline__ void p0_transpose_item(const float* W, int K, int N, bf16* WT, LAS float* scr, int item, int lane) {
;     const int nblk = N / 32, kb = item / nblk, nb = item % nblk, k0 = 64 * kb, n0 = 32 * nb;
; #pragma unroll 8
;     for (int i = 0; i < 32; ++i) { const int kk = 2 * i + (lane >> 5); scr[kk * 33 + (lane & 31)] = ((const GAS float*)W)[(size_t)(k0 + kk) * N + n0 + (lane & 31)]; }
; __device__ __forceinline__ void phase_prologue(Frame& F) {
;     ...
;         if (r < I_IN) { p0_transpose_item(INP(6) + (size_t)l * D * DIN, D, DIN, (bf16*)(ws_ + WS_WIN + l * SZ_WIN), scr, r, lane); continue; } r -= I_IN;
.LBB0_52:
	s_mov_b32 s98, s29
	s_bfe_u32 s99, s98, 0x50003
	s_lshr_b32 s100, s98, 8
	s_and_b32 s98, s98, 7
	s_lshl_b32 s100, s100, 3
	s_mul_i32 s99, s99, 0x148
	s_add_i32 s99, s99, s100
	s_add_i32 s99, s99, s98
	s_mov_b32 s29, s99
	s_load_dwordx2 s[8:9], s[10:11], 0x30
	s_mul_i32 s12, s6, 0x5200000
	s_mul_hi_i32 s7, s6, 0x5200000
	s_mul_i32 s13, s29, 0xffffc7cf
	s_waitcnt lgkmcnt(0)
	s_add_u32 s30, s8, s12
	s_addc_u32 s7, s9, s7
	s_lshr_b32 s8, s13, 16
	s_add_i32 s8, s8, s29
	s_sext_i32_i16 s9, s8
	s_ashr_i32 s9, s9, 8
	s_bfe_u32 s8, s8, 0x1000f
	s_add_i32 s8, s9, s8
	s_mul_i32 s9, s8, 0x148
	s_sub_i32 s9, s29, s9
	s_sext_i32_i16 s9, s9
	s_lshl_b32 s12, s8, 6
	s_lshl_b32 s8, s9, 5
	s_ashr_i32 s9, s8, 31
	s_lshl_b64 s[14:15], s[8:9], 2
	s_add_u32 s14, s30, s14
	s_addc_u32 s15, s7, s15
	v_lshl_add_u64 v[22:23], s[14:15], 0, v[2:3]
	v_add_u32_e32 v19, s12, v1
	v_add_u32_e32 v24, s12, v0
	v_add_u32_e32 v21, s12, v5
	v_add_u32_e32 v26, s12, v8
	v_add_u32_e32 v25, s12, v7
	v_add_u32_e32 v28, s12, v10
	v_add_u32_e32 v27, s12, v9
	v_add_u32_e32 v30, s12, v12
	v_add_u32_e32 v29, s12, v11
	v_add_u32_e32 v32, s12, v14
	v_add_u32_e32 v31, s12, v13
	v_add_u32_e32 v34, s12, v16
	s_mov_b32 s7, 1
	s_mov_b32 s9, 0
	s_mov_b32 s13, 32
	v_add_u32_e32 v33, s12, v15
	v_add_u32_e32 v36, s12, v18
	v_add_u32_e32 v35, s12, v17
	v_add_u32_e32 v38, s12, v20
